# v122 + l2norm sum of squares via packed-FMA chain + P2 step-2 per-SIMD-pair tile balance 5/5/5/5
# speedup vs baseline: 1.0205x; 1.0009x over previous
; #define LAS __attribute__((address_space(3)))
; template <int SKIP>
; __device__ __forceinline__ void p2_chunk_prep_fast(Frame& F, const Args& a) {
;     ...
;             f32x4 cwr[8];
; #pragma unroll
;             for (int kk = 0; kk < 4; ++kk) { cwr[2 * kk] = *(const LAS f32x4*)(cw + kk * 384 + which * 128 + d8); cwr[2 * kk + 1] = *(const LAS f32x4*)(cw + kk * 384 + which * 128 + d8 + 4); }
; #pragma unroll
;             for (int hb = 0; hb < 2; ++hb) {
;                 unsigned tr[4][4];
; #pragma unroll
;                 for (int i4 = 0; i4 < 4; ++i4) { const int ii = 4 * hb + i4;
;                     float v[8];
; #pragma unroll
;                     for (int j = 0; j < 8; ++j) v[j] = 0.f;
; #pragma unroll
;                     for (int kk = 0; kk < 4; ++kk) { f32x4 x0, x1; pg8::unpack8(raw.x[ii + kk], x0, x1);
; #pragma unroll
;                         for (int j = 0; j < 4; ++j) { v[j] += cwr[2 * kk][j] * x0[j]; v[4 + j] += cwr[2 * kk + 1][j] * x1[j]; } }
.LBB0_629:
	v_readlane_b32 s6, v255, 38
	v_readlane_b32 s7, v255, 19
	v_lshl_add_u32 v104, v119, 2, s6
	ds_read_b128 v[46:49], v104 offset:0
	ds_read_b128 v[50:53], v104 offset:16
	ds_read_b128 v[54:57], v104 offset:1536
	ds_read_b128 v[58:61], v104 offset:1552
	ds_read_b128 v[62:65], v104 offset:3072
	ds_read_b128 v[66:69], v104 offset:3088
	ds_read_b128 v[70:73], v104 offset:4608
	ds_read_b128 v[74:77], v104 offset:4624
	s_lshr_b32 s7, s7, 1
	v_readlane_b32 s8, v255, 43
	v_readlane_b32 s9, v255, 45
	s_mov_b32 s88, 0x5040100
	s_mov_b32 s89, 0x7060302
	s_movk_i32 s85, 0x880
	v_mov_b32_e32 v100, 0xbfb8aa3b
	v_mov_b32_e32 v101, 0xbfb8aa3b
	v_mov_b32_e32 v152, 1.0
	v_mov_b32_e32 v153, 1.0
	v_lshl_add_u32 v102, v83, 4, s8
	v_mad_u32_u24 v102, v78, s85, v102
	v_xor_b32_e32 v103, v78, v117
	v_lshlrev_b32_e32 v103, 4, v103
	v_and_b32_e32 v103, 0x70, v103
	v_add_u32_e32 v103, s9, v103
	s_movk_i32 s85, 0x480
	v_mad_u32_u24 v103, v83, s85, v103
	s_waitcnt vmcnt(0)
	v_lshlrev_b32_e32 v160, 16, v30
	v_and_b32_e32 v161, 0xffff0000, v30
	v_lshlrev_b32_e32 v162, 16, v31
	v_and_b32_e32 v163, 0xffff0000, v31
	v_lshlrev_b32_e32 v164, 16, v32
	v_and_b32_e32 v165, 0xffff0000, v32
	v_lshlrev_b32_e32 v166, 16, v33
	v_and_b32_e32 v167, 0xffff0000, v33
	v_lshlrev_b32_e32 v168, 16, v38
	v_and_b32_e32 v169, 0xffff0000, v38
	v_lshlrev_b32_e32 v170, 16, v39
	v_and_b32_e32 v171, 0xffff0000, v39
	v_lshlrev_b32_e32 v172, 16, v40
	v_and_b32_e32 v173, 0xffff0000, v40
	v_lshlrev_b32_e32 v174, 16, v41
	v_and_b32_e32 v175, 0xffff0000, v41
	v_lshlrev_b32_e32 v176, 16, v34
	v_and_b32_e32 v177, 0xffff0000, v34
	v_lshlrev_b32_e32 v178, 16, v35
	v_and_b32_e32 v179, 0xffff0000, v35
	v_lshlrev_b32_e32 v180, 16, v36
	v_and_b32_e32 v181, 0xffff0000, v36
	v_lshlrev_b32_e32 v182, 16, v37
	v_and_b32_e32 v183, 0xffff0000, v37
	v_lshlrev_b32_e32 v184, 16, v42
	v_and_b32_e32 v185, 0xffff0000, v42
	v_lshlrev_b32_e32 v186, 16, v43
	v_and_b32_e32 v187, 0xffff0000, v43
	v_lshlrev_b32_e32 v188, 16, v44
	v_and_b32_e32 v189, 0xffff0000, v44
	v_lshlrev_b32_e32 v190, 16, v45
	v_and_b32_e32 v191, 0xffff0000, v45
	v_lshlrev_b32_e32 v192, 16, v26
	v_and_b32_e32 v193, 0xffff0000, v26
	v_lshlrev_b32_e32 v194, 16, v27
	v_and_b32_e32 v195, 0xffff0000, v27
	v_lshlrev_b32_e32 v196, 16, v28
	v_and_b32_e32 v197, 0xffff0000, v28
	v_lshlrev_b32_e32 v198, 16, v29
	v_and_b32_e32 v199, 0xffff0000, v29
	v_lshlrev_b32_e32 v200, 16, v22
	v_and_b32_e32 v201, 0xffff0000, v22
	v_lshlrev_b32_e32 v202, 16, v23
	v_and_b32_e32 v203, 0xffff0000, v23
	v_lshlrev_b32_e32 v204, 16, v24
	v_and_b32_e32 v205, 0xffff0000, v24
	v_lshlrev_b32_e32 v206, 16, v25
	v_and_b32_e32 v207, 0xffff0000, v25
	v_lshlrev_b32_e32 v208, 16, v18
	v_and_b32_e32 v209, 0xffff0000, v18
	v_lshlrev_b32_e32 v210, 16, v19
	v_and_b32_e32 v211, 0xffff0000, v19
	v_lshlrev_b32_e32 v212, 16, v20
	v_and_b32_e32 v213, 0xffff0000, v20
	v_lshlrev_b32_e32 v214, 16, v21
	v_and_b32_e32 v215, 0xffff0000, v21
	v_lshlrev_b32_e32 v216, 16, v14
	v_and_b32_e32 v217, 0xffff0000, v14
	v_lshlrev_b32_e32 v218, 16, v15
	v_and_b32_e32 v219, 0xffff0000, v15
	v_lshlrev_b32_e32 v220, 16, v16
	v_and_b32_e32 v221, 0xffff0000, v16
	v_lshlrev_b32_e32 v222, 16, v17
	v_and_b32_e32 v223, 0xffff0000, v17
	v_lshlrev_b32_e32 v224, 16, v10
	v_and_b32_e32 v225, 0xffff0000, v10
	v_lshlrev_b32_e32 v226, 16, v11
	v_and_b32_e32 v227, 0xffff0000, v11
	v_lshlrev_b32_e32 v228, 16, v12
	v_and_b32_e32 v229, 0xffff0000, v12
	v_lshlrev_b32_e32 v230, 16, v13
	v_and_b32_e32 v231, 0xffff0000, v13
	v_lshlrev_b32_e32 v232, 16, v6
	v_and_b32_e32 v233, 0xffff0000, v6
	v_lshlrev_b32_e32 v234, 16, v7
	v_and_b32_e32 v235, 0xffff0000, v7
	v_lshlrev_b32_e32 v236, 16, v8
	v_and_b32_e32 v237, 0xffff0000, v8
	v_lshlrev_b32_e32 v238, 16, v9
	v_and_b32_e32 v239, 0xffff0000, v9
	v_lshlrev_b32_e32 v240, 16, v2
	v_and_b32_e32 v241, 0xffff0000, v2
	v_lshlrev_b32_e32 v242, 16, v3
	v_and_b32_e32 v243, 0xffff0000, v3
	v_lshlrev_b32_e32 v244, 16, v4
	v_and_b32_e32 v245, 0xffff0000, v4
	v_lshlrev_b32_e32 v246, 16, v5
	v_and_b32_e32 v247, 0xffff0000, v5
	s_waitcnt lgkmcnt(0)
; __device__ __forceinline__ float fast_sigmoid(float x) { return __builtin_amdgcn_rcpf(1.f + __builtin_amdgcn_exp2f(-1.4426950408889634f * x)); }
; template <int SKIP>
; __device__ __forceinline__ void p2_chunk_prep_fast(Frame& F, const Args& a) {
;     ...
;                 for (int i4 = 0; i4 < 4; ++i4) { const int ii = 4 * hb + i4;
;                     float v[8];
; #pragma unroll
;                     for (int j = 0; j < 8; ++j) v[j] = 0.f;
; #pragma unroll
;                     for (int kk = 0; kk < 4; ++kk) { f32x4 x0, x1; pg8::unpack8(raw.x[ii + kk], x0, x1);
; #pragma unroll
;                         for (int j = 0; j < 4; ++j) { v[j] += cwr[2 * kk][j] * x0[j]; v[4 + j] += cwr[2 * kk + 1][j] * x1[j]; } }
; #pragma unroll
;                     for (int j = 0; j < 8; ++j) v[j] = v[j] * pg8::fast_sigmoid(v[j]);
;                     if (which < 2) { float ss = 0.f;
; #pragma unroll
;                         for (int j = 0; j < 8; ++j) ss += v[j] * v[j];
;                         ss += __shfl_xor(ss, 1); ss += __shfl_xor(ss, 2); ss += __shfl_xor(ss, 4); ss += __shfl_xor(ss, 8);
;                         const float rs = rsqrtf(ss + EPS) * (which == 0 ? 0.08838834764831845f : 1.f);
; #pragma unroll
;                         for (int j = 0; j < 8; ++j) v[j] *= rs; }
	v_pk_fma_f32 v[84:85], v[46:47], v[160:161], 0 op_sel_hi:[1,1,0]
	v_pk_fma_f32 v[92:93], v[46:47], v[168:169], 0 op_sel_hi:[1,1,0]
	v_pk_fma_f32 v[86:87], v[48:49], v[162:163], 0 op_sel_hi:[1,1,0]
	v_pk_fma_f32 v[94:95], v[48:49], v[170:171], 0 op_sel_hi:[1,1,0]
	v_pk_fma_f32 v[88:89], v[50:51], v[164:165], 0 op_sel_hi:[1,1,0]
	v_pk_fma_f32 v[96:97], v[50:51], v[172:173], 0 op_sel_hi:[1,1,0]
	v_pk_fma_f32 v[90:91], v[52:53], v[166:167], 0 op_sel_hi:[1,1,0]
	v_pk_fma_f32 v[98:99], v[52:53], v[174:175], 0 op_sel_hi:[1,1,0]
	v_pk_fma_f32 v[84:85], v[54:55], v[168:169], v[84:85]
	v_pk_fma_f32 v[92:93], v[54:55], v[176:177], v[92:93]
	v_pk_fma_f32 v[86:87], v[56:57], v[170:171], v[86:87]
	v_pk_fma_f32 v[94:95], v[56:57], v[178:179], v[94:95]
	v_pk_fma_f32 v[88:89], v[58:59], v[172:173], v[88:89]
	v_pk_fma_f32 v[96:97], v[58:59], v[180:181], v[96:97]
	v_pk_fma_f32 v[90:91], v[60:61], v[174:175], v[90:91]
	v_pk_fma_f32 v[98:99], v[60:61], v[182:183], v[98:99]
	v_pk_fma_f32 v[84:85], v[62:63], v[176:177], v[84:85]
	v_pk_fma_f32 v[92:93], v[62:63], v[184:185], v[92:93]
	v_pk_fma_f32 v[86:87], v[64:65], v[178:179], v[86:87]
	v_pk_fma_f32 v[94:95], v[64:65], v[186:187], v[94:95]
	v_pk_fma_f32 v[88:89], v[66:67], v[180:181], v[88:89]
	v_pk_fma_f32 v[96:97], v[66:67], v[188:189], v[96:97]
	v_pk_fma_f32 v[90:91], v[68:69], v[182:183], v[90:91]
	v_pk_fma_f32 v[98:99], v[68:69], v[190:191], v[98:99]
	v_pk_fma_f32 v[84:85], v[70:71], v[184:185], v[84:85]
	v_pk_fma_f32 v[92:93], v[70:71], v[192:193], v[92:93]
	v_pk_fma_f32 v[86:87], v[72:73], v[186:187], v[86:87]
	v_pk_fma_f32 v[94:95], v[72:73], v[194:195], v[94:95]
	v_pk_fma_f32 v[88:89], v[74:75], v[188:189], v[88:89]
	v_pk_fma_f32 v[96:97], v[74:75], v[196:197], v[96:97]
	v_pk_fma_f32 v[90:91], v[76:77], v[190:191], v[90:91]
	v_pk_fma_f32 v[98:99], v[76:77], v[198:199], v[98:99]
	v_pk_mul_f32 v[18:19], v[84:85], v[100:101]
	v_pk_mul_f32 v[26:27], v[92:93], v[100:101]
	v_pk_mul_f32 v[20:21], v[86:87], v[100:101]
	v_pk_mul_f32 v[28:29], v[94:95], v[100:101]
	v_pk_mul_f32 v[22:23], v[88:89], v[100:101]
	v_pk_mul_f32 v[30:31], v[96:97], v[100:101]
	v_pk_mul_f32 v[24:25], v[90:91], v[100:101]
	v_pk_mul_f32 v[32:33], v[98:99], v[100:101]
	v_exp_f32_e32 v18, v18
	v_exp_f32_e32 v26, v26
	v_exp_f32_e32 v19, v19
	v_exp_f32_e32 v27, v27
	v_exp_f32_e32 v20, v20
	v_exp_f32_e32 v28, v28
	v_exp_f32_e32 v21, v21
	v_exp_f32_e32 v29, v29
	v_exp_f32_e32 v22, v22
	v_exp_f32_e32 v30, v30
	v_exp_f32_e32 v23, v23
	v_exp_f32_e32 v31, v31
	v_exp_f32_e32 v24, v24
	v_exp_f32_e32 v32, v32
	v_exp_f32_e32 v25, v25
	v_exp_f32_e32 v33, v33
	v_pk_add_f32 v[18:19], v[18:19], v[152:153]
	v_pk_add_f32 v[26:27], v[26:27], v[152:153]
	v_pk_add_f32 v[20:21], v[20:21], v[152:153]
	v_pk_add_f32 v[28:29], v[28:29], v[152:153]
	v_pk_add_f32 v[22:23], v[22:23], v[152:153]
	v_pk_add_f32 v[30:31], v[30:31], v[152:153]
	v_pk_add_f32 v[24:25], v[24:25], v[152:153]
	v_pk_add_f32 v[32:33], v[32:33], v[152:153]
	v_rcp_f32_e32 v18, v18
	v_rcp_f32_e32 v26, v26
	v_rcp_f32_e32 v19, v19
	v_rcp_f32_e32 v27, v27
	v_rcp_f32_e32 v20, v20
	v_rcp_f32_e32 v28, v28
	v_rcp_f32_e32 v21, v21
	v_rcp_f32_e32 v29, v29
	v_rcp_f32_e32 v22, v22
	v_rcp_f32_e32 v30, v30
	v_rcp_f32_e32 v23, v23
	v_rcp_f32_e32 v31, v31
	v_rcp_f32_e32 v24, v24
	v_rcp_f32_e32 v32, v32
	v_rcp_f32_e32 v25, v25
	v_rcp_f32_e32 v33, v33
	v_pk_mul_f32 v[84:85], v[84:85], v[18:19]
	v_pk_mul_f32 v[92:93], v[92:93], v[26:27]
	v_pk_mul_f32 v[86:87], v[86:87], v[20:21]
	v_pk_mul_f32 v[94:95], v[94:95], v[28:29]
	v_pk_mul_f32 v[88:89], v[88:89], v[22:23]
	v_pk_mul_f32 v[96:97], v[96:97], v[30:31]
	v_pk_mul_f32 v[90:91], v[90:91], v[24:25]
	v_pk_mul_f32 v[98:99], v[98:99], v[32:33]
	s_cmp_lt_u32 s7, 2
	s_cbranch_scc0 .Lp2c_nonorm_1
	v_pk_mul_f32 v[18:19], v[84:85], v[84:85]
	v_pk_mul_f32 v[26:27], v[92:93], v[92:93]
	v_pk_fma_f32 v[18:19], v[86:87], v[86:87], v[18:19]
	v_pk_fma_f32 v[26:27], v[94:95], v[94:95], v[26:27]
	v_pk_fma_f32 v[18:19], v[88:89], v[88:89], v[18:19]
	v_pk_fma_f32 v[26:27], v[96:97], v[96:97], v[26:27]
	v_pk_fma_f32 v[18:19], v[90:91], v[90:91], v[18:19]
	v_pk_fma_f32 v[26:27], v[98:99], v[98:99], v[26:27]
	v_add_f32_e32 v34, v18, v19
	v_add_f32_e32 v40, v26, v27
	s_nop 0
	v_add_f32_dpp v34, v34, v34 quad_perm:[1,0,3,2] row_mask:0xf bank_mask:0xf
	v_add_f32_dpp v40, v40, v40 quad_perm:[1,0,3,2] row_mask:0xf bank_mask:0xf
	s_nop 0
	v_add_f32_dpp v34, v34, v34 quad_perm:[2,3,0,1] row_mask:0xf bank_mask:0xf
	v_add_f32_dpp v40, v40, v40 quad_perm:[2,3,0,1] row_mask:0xf bank_mask:0xf
	s_nop 0
	v_add_f32_dpp v34, v34, v34 row_half_mirror row_mask:0xf bank_mask:0xf
	v_add_f32_dpp v40, v40, v40 row_half_mirror row_mask:0xf bank_mask:0xf
	s_nop 0
	v_add_f32_dpp v34, v34, v34 row_mirror row_mask:0xf bank_mask:0xf
	v_add_f32_dpp v40, v40, v40 row_mirror row_mask:0xf bank_mask:0xf
	v_add_f32_e32 v34, 0x358637bd, v34
	v_add_f32_e32 v40, 0x358637bd, v40
	v_rsq_f32_e32 v34, v34
	v_rsq_f32_e32 v40, v40
	s_nop 0
	v_mul_f32_e32 v34, v1, v34
	v_mul_f32_e32 v40, v1, v40
	s_nop 0
	v_pk_mul_f32 v[84:85], v[84:85], v[34:35] op_sel_hi:[1,0]
	v_pk_mul_f32 v[86:87], v[86:87], v[34:35] op_sel_hi:[1,0]
	v_pk_mul_f32 v[88:89], v[88:89], v[34:35] op_sel_hi:[1,0]
	v_pk_mul_f32 v[90:91], v[90:91], v[34:35] op_sel_hi:[1,0]
	v_pk_mul_f32 v[92:93], v[92:93], v[40:41] op_sel_hi:[1,0]
	v_pk_mul_f32 v[94:95], v[94:95], v[40:41] op_sel_hi:[1,0]
	v_pk_mul_f32 v[96:97], v[96:97], v[40:41] op_sel_hi:[1,0]
	v_pk_mul_f32 v[98:99], v[98:99], v[40:41] op_sel_hi:[1,0]

; __device__ __forceinline__ float fast_sigmoid(float x) { return __builtin_amdgcn_rcpf(1.f + __builtin_amdgcn_exp2f(-1.4426950408889634f * x)); }
; template <int SKIP>
; __device__ __forceinline__ void p2_chunk_prep_fast(Frame& F, const Args& a) {
;     ...
;                 for (int i4 = 0; i4 < 4; ++i4) { const int ii = 4 * hb + i4;
;                     float v[8];
; #pragma unroll
;                     for (int j = 0; j < 8; ++j) v[j] = 0.f;
; #pragma unroll
;                     for (int kk = 0; kk < 4; ++kk) { f32x4 x0, x1; pg8::unpack8(raw.x[ii + kk], x0, x1);
; #pragma unroll
;                         for (int j = 0; j < 4; ++j) { v[j] += cwr[2 * kk][j] * x0[j]; v[4 + j] += cwr[2 * kk + 1][j] * x1[j]; } }
; #pragma unroll
;                     for (int j = 0; j < 8; ++j) v[j] = v[j] * pg8::fast_sigmoid(v[j]);
;                     if (which < 2) { float ss = 0.f;
; #pragma unroll
;                         for (int j = 0; j < 8; ++j) ss += v[j] * v[j];
;                         ss += __shfl_xor(ss, 1); ss += __shfl_xor(ss, 2); ss += __shfl_xor(ss, 4); ss += __shfl_xor(ss, 8);
;                         const float rs = rsqrtf(ss + EPS) * (which == 0 ? 0.08838834764831845f : 1.f);
; #pragma unroll
;                         for (int j = 0; j < 8; ++j) v[j] *= rs; }
.Lp2c_norow_2:
	v_pk_fma_f32 v[84:85], v[46:47], v[176:177], 0 op_sel_hi:[1,1,0]
	v_pk_fma_f32 v[92:93], v[46:47], v[184:185], 0 op_sel_hi:[1,1,0]
	v_pk_fma_f32 v[86:87], v[48:49], v[178:179], 0 op_sel_hi:[1,1,0]
	v_pk_fma_f32 v[94:95], v[48:49], v[186:187], 0 op_sel_hi:[1,1,0]
	v_pk_fma_f32 v[88:89], v[50:51], v[180:181], 0 op_sel_hi:[1,1,0]
	v_pk_fma_f32 v[96:97], v[50:51], v[188:189], 0 op_sel_hi:[1,1,0]
	v_pk_fma_f32 v[90:91], v[52:53], v[182:183], 0 op_sel_hi:[1,1,0]
	v_pk_fma_f32 v[98:99], v[52:53], v[190:191], 0 op_sel_hi:[1,1,0]
	v_pk_fma_f32 v[84:85], v[54:55], v[184:185], v[84:85]
	v_pk_fma_f32 v[92:93], v[54:55], v[192:193], v[92:93]
	v_pk_fma_f32 v[86:87], v[56:57], v[186:187], v[86:87]
	v_pk_fma_f32 v[94:95], v[56:57], v[194:195], v[94:95]
	v_pk_fma_f32 v[88:89], v[58:59], v[188:189], v[88:89]
	v_pk_fma_f32 v[96:97], v[58:59], v[196:197], v[96:97]
	v_pk_fma_f32 v[90:91], v[60:61], v[190:191], v[90:91]
	v_pk_fma_f32 v[98:99], v[60:61], v[198:199], v[98:99]
	v_pk_fma_f32 v[84:85], v[62:63], v[192:193], v[84:85]
	v_pk_fma_f32 v[92:93], v[62:63], v[200:201], v[92:93]
	v_pk_fma_f32 v[86:87], v[64:65], v[194:195], v[86:87]
	v_pk_fma_f32 v[94:95], v[64:65], v[202:203], v[94:95]
	v_pk_fma_f32 v[88:89], v[66:67], v[196:197], v[88:89]
	v_pk_fma_f32 v[96:97], v[66:67], v[204:205], v[96:97]
	v_pk_fma_f32 v[90:91], v[68:69], v[198:199], v[90:91]
	v_pk_fma_f32 v[98:99], v[68:69], v[206:207], v[98:99]
	v_pk_fma_f32 v[84:85], v[70:71], v[200:201], v[84:85]
	v_pk_fma_f32 v[92:93], v[70:71], v[208:209], v[92:93]
	v_pk_fma_f32 v[86:87], v[72:73], v[202:203], v[86:87]
	v_pk_fma_f32 v[94:95], v[72:73], v[210:211], v[94:95]
	v_pk_fma_f32 v[88:89], v[74:75], v[204:205], v[88:89]
	v_pk_fma_f32 v[96:97], v[74:75], v[212:213], v[96:97]
	v_pk_fma_f32 v[90:91], v[76:77], v[206:207], v[90:91]
	v_pk_fma_f32 v[98:99], v[76:77], v[214:215], v[98:99]
	v_pk_mul_f32 v[18:19], v[84:85], v[100:101]
	v_pk_mul_f32 v[26:27], v[92:93], v[100:101]
	v_pk_mul_f32 v[20:21], v[86:87], v[100:101]
	v_pk_mul_f32 v[28:29], v[94:95], v[100:101]
	v_pk_mul_f32 v[22:23], v[88:89], v[100:101]
	v_pk_mul_f32 v[30:31], v[96:97], v[100:101]
	v_pk_mul_f32 v[24:25], v[90:91], v[100:101]
	v_pk_mul_f32 v[32:33], v[98:99], v[100:101]
	v_exp_f32_e32 v18, v18
	v_exp_f32_e32 v26, v26
	v_exp_f32_e32 v19, v19
	v_exp_f32_e32 v27, v27
	v_exp_f32_e32 v20, v20
	v_exp_f32_e32 v28, v28
	v_exp_f32_e32 v21, v21
	v_exp_f32_e32 v29, v29
	v_exp_f32_e32 v22, v22
	v_exp_f32_e32 v30, v30
	v_exp_f32_e32 v23, v23
	v_exp_f32_e32 v31, v31
	v_exp_f32_e32 v24, v24
	v_exp_f32_e32 v32, v32
	v_exp_f32_e32 v25, v25
	v_exp_f32_e32 v33, v33
	v_pk_add_f32 v[18:19], v[18:19], v[152:153]
	v_pk_add_f32 v[26:27], v[26:27], v[152:153]
	v_pk_add_f32 v[20:21], v[20:21], v[152:153]
	v_pk_add_f32 v[28:29], v[28:29], v[152:153]
	v_pk_add_f32 v[22:23], v[22:23], v[152:153]
	v_pk_add_f32 v[30:31], v[30:31], v[152:153]
	v_pk_add_f32 v[24:25], v[24:25], v[152:153]
	v_pk_add_f32 v[32:33], v[32:33], v[152:153]
	v_rcp_f32_e32 v18, v18
	v_rcp_f32_e32 v26, v26
	v_rcp_f32_e32 v19, v19
	v_rcp_f32_e32 v27, v27
	v_rcp_f32_e32 v20, v20
	v_rcp_f32_e32 v28, v28
	v_rcp_f32_e32 v21, v21
	v_rcp_f32_e32 v29, v29
	v_rcp_f32_e32 v22, v22
	v_rcp_f32_e32 v30, v30
	v_rcp_f32_e32 v23, v23
	v_rcp_f32_e32 v31, v31
	v_rcp_f32_e32 v24, v24
	v_rcp_f32_e32 v32, v32
	v_rcp_f32_e32 v25, v25
	v_rcp_f32_e32 v33, v33
	v_pk_mul_f32 v[84:85], v[84:85], v[18:19]
	v_pk_mul_f32 v[92:93], v[92:93], v[26:27]
	v_pk_mul_f32 v[86:87], v[86:87], v[20:21]
	v_pk_mul_f32 v[94:95], v[94:95], v[28:29]
	v_pk_mul_f32 v[88:89], v[88:89], v[22:23]
	v_pk_mul_f32 v[96:97], v[96:97], v[30:31]
	v_pk_mul_f32 v[90:91], v[90:91], v[24:25]
	v_pk_mul_f32 v[98:99], v[98:99], v[32:33]
	s_cmp_lt_u32 s7, 2
	s_cbranch_scc0 .Lp2c_nonorm_3
	v_pk_mul_f32 v[18:19], v[84:85], v[84:85]
	v_pk_mul_f32 v[26:27], v[92:93], v[92:93]
	v_pk_fma_f32 v[18:19], v[86:87], v[86:87], v[18:19]
	v_pk_fma_f32 v[26:27], v[94:95], v[94:95], v[26:27]
	v_pk_fma_f32 v[18:19], v[88:89], v[88:89], v[18:19]
	v_pk_fma_f32 v[26:27], v[96:97], v[96:97], v[26:27]
	v_pk_fma_f32 v[18:19], v[90:91], v[90:91], v[18:19]
	v_pk_fma_f32 v[26:27], v[98:99], v[98:99], v[26:27]
	v_add_f32_e32 v34, v18, v19
	v_add_f32_e32 v40, v26, v27
	s_nop 0
	v_add_f32_dpp v34, v34, v34 quad_perm:[1,0,3,2] row_mask:0xf bank_mask:0xf
	v_add_f32_dpp v40, v40, v40 quad_perm:[1,0,3,2] row_mask:0xf bank_mask:0xf
	s_nop 0
	v_add_f32_dpp v34, v34, v34 quad_perm:[2,3,0,1] row_mask:0xf bank_mask:0xf
	v_add_f32_dpp v40, v40, v40 quad_perm:[2,3,0,1] row_mask:0xf bank_mask:0xf
	s_nop 0
	v_add_f32_dpp v34, v34, v34 row_half_mirror row_mask:0xf bank_mask:0xf
	v_add_f32_dpp v40, v40, v40 row_half_mirror row_mask:0xf bank_mask:0xf
	s_nop 0
	v_add_f32_dpp v34, v34, v34 row_mirror row_mask:0xf bank_mask:0xf
	v_add_f32_dpp v40, v40, v40 row_mirror row_mask:0xf bank_mask:0xf
	v_add_f32_e32 v34, 0x358637bd, v34
	v_add_f32_e32 v40, 0x358637bd, v40
	v_rsq_f32_e32 v34, v34
	v_rsq_f32_e32 v40, v40
	s_nop 0
	v_mul_f32_e32 v34, v1, v34
	v_mul_f32_e32 v40, v1, v40
	s_nop 0
	v_pk_mul_f32 v[84:85], v[84:85], v[34:35] op_sel_hi:[1,0]
	v_pk_mul_f32 v[86:87], v[86:87], v[34:35] op_sel_hi:[1,0]
	v_pk_mul_f32 v[88:89], v[88:89], v[34:35] op_sel_hi:[1,0]
	v_pk_mul_f32 v[90:91], v[90:91], v[34:35] op_sel_hi:[1,0]
	v_pk_mul_f32 v[92:93], v[92:93], v[40:41] op_sel_hi:[1,0]
	v_pk_mul_f32 v[94:95], v[94:95], v[40:41] op_sel_hi:[1,0]
	v_pk_mul_f32 v[96:97], v[96:97], v[40:41] op_sel_hi:[1,0]
	v_pk_mul_f32 v[98:99], v[98:99], v[40:41] op_sel_hi:[1,0]

; __device__ __forceinline__ float fast_sigmoid(float x) { return __builtin_amdgcn_rcpf(1.f + __builtin_amdgcn_exp2f(-1.4426950408889634f * x)); }
; template <int SKIP>
; __device__ __forceinline__ void p2_chunk_prep_fast(Frame& F, const Args& a) {
;     ...
;                 for (int i4 = 0; i4 < 4; ++i4) { const int ii = 4 * hb + i4;
;                     float v[8];
; #pragma unroll
;                     for (int j = 0; j < 8; ++j) v[j] = 0.f;
; #pragma unroll
;                     for (int kk = 0; kk < 4; ++kk) { f32x4 x0, x1; pg8::unpack8(raw.x[ii + kk], x0, x1);
; #pragma unroll
;                         for (int j = 0; j < 4; ++j) { v[j] += cwr[2 * kk][j] * x0[j]; v[4 + j] += cwr[2 * kk + 1][j] * x1[j]; } }
; #pragma unroll
;                     for (int j = 0; j < 8; ++j) v[j] = v[j] * pg8::fast_sigmoid(v[j]);
;                     if (which < 2) { float ss = 0.f;
; #pragma unroll
;                         for (int j = 0; j < 8; ++j) ss += v[j] * v[j];
;                         ss += __shfl_xor(ss, 1); ss += __shfl_xor(ss, 2); ss += __shfl_xor(ss, 4); ss += __shfl_xor(ss, 8);
;                         const float rs = rsqrtf(ss + EPS) * (which == 0 ? 0.08838834764831845f : 1.f);
; #pragma unroll
;                         for (int j = 0; j < 8; ++j) v[j] *= rs; }
.Lp2c_notr_5:
	v_pk_fma_f32 v[84:85], v[46:47], v[192:193], 0 op_sel_hi:[1,1,0]
	v_pk_fma_f32 v[92:93], v[46:47], v[200:201], 0 op_sel_hi:[1,1,0]
	v_pk_fma_f32 v[86:87], v[48:49], v[194:195], 0 op_sel_hi:[1,1,0]
	v_pk_fma_f32 v[94:95], v[48:49], v[202:203], 0 op_sel_hi:[1,1,0]
	v_pk_fma_f32 v[88:89], v[50:51], v[196:197], 0 op_sel_hi:[1,1,0]
	v_pk_fma_f32 v[96:97], v[50:51], v[204:205], 0 op_sel_hi:[1,1,0]
	v_pk_fma_f32 v[90:91], v[52:53], v[198:199], 0 op_sel_hi:[1,1,0]
	v_pk_fma_f32 v[98:99], v[52:53], v[206:207], 0 op_sel_hi:[1,1,0]
	v_pk_fma_f32 v[84:85], v[54:55], v[200:201], v[84:85]
	v_pk_fma_f32 v[92:93], v[54:55], v[208:209], v[92:93]
	v_pk_fma_f32 v[86:87], v[56:57], v[202:203], v[86:87]
	v_pk_fma_f32 v[94:95], v[56:57], v[210:211], v[94:95]
	v_pk_fma_f32 v[88:89], v[58:59], v[204:205], v[88:89]
	v_pk_fma_f32 v[96:97], v[58:59], v[212:213], v[96:97]
	v_pk_fma_f32 v[90:91], v[60:61], v[206:207], v[90:91]
	v_pk_fma_f32 v[98:99], v[60:61], v[214:215], v[98:99]
	v_pk_fma_f32 v[84:85], v[62:63], v[208:209], v[84:85]
	v_pk_fma_f32 v[92:93], v[62:63], v[216:217], v[92:93]
	v_pk_fma_f32 v[86:87], v[64:65], v[210:211], v[86:87]
	v_pk_fma_f32 v[94:95], v[64:65], v[218:219], v[94:95]
	v_pk_fma_f32 v[88:89], v[66:67], v[212:213], v[88:89]
	v_pk_fma_f32 v[96:97], v[66:67], v[220:221], v[96:97]
	v_pk_fma_f32 v[90:91], v[68:69], v[214:215], v[90:91]
	v_pk_fma_f32 v[98:99], v[68:69], v[222:223], v[98:99]
	v_pk_fma_f32 v[84:85], v[70:71], v[216:217], v[84:85]
	v_pk_fma_f32 v[92:93], v[70:71], v[224:225], v[92:93]
	v_pk_fma_f32 v[86:87], v[72:73], v[218:219], v[86:87]
	v_pk_fma_f32 v[94:95], v[72:73], v[226:227], v[94:95]
	v_pk_fma_f32 v[88:89], v[74:75], v[220:221], v[88:89]
	v_pk_fma_f32 v[96:97], v[74:75], v[228:229], v[96:97]
	v_pk_fma_f32 v[90:91], v[76:77], v[222:223], v[90:91]
	v_pk_fma_f32 v[98:99], v[76:77], v[230:231], v[98:99]
	v_pk_mul_f32 v[18:19], v[84:85], v[100:101]
	v_pk_mul_f32 v[26:27], v[92:93], v[100:101]
	v_pk_mul_f32 v[20:21], v[86:87], v[100:101]
	v_pk_mul_f32 v[28:29], v[94:95], v[100:101]
	v_pk_mul_f32 v[22:23], v[88:89], v[100:101]
	v_pk_mul_f32 v[30:31], v[96:97], v[100:101]
	v_pk_mul_f32 v[24:25], v[90:91], v[100:101]
	v_pk_mul_f32 v[32:33], v[98:99], v[100:101]
	v_exp_f32_e32 v18, v18
	v_exp_f32_e32 v26, v26
	v_exp_f32_e32 v19, v19
	v_exp_f32_e32 v27, v27
	v_exp_f32_e32 v20, v20
	v_exp_f32_e32 v28, v28
	v_exp_f32_e32 v21, v21
	v_exp_f32_e32 v29, v29
	v_exp_f32_e32 v22, v22
	v_exp_f32_e32 v30, v30
	v_exp_f32_e32 v23, v23
	v_exp_f32_e32 v31, v31
	v_exp_f32_e32 v24, v24
	v_exp_f32_e32 v32, v32
	v_exp_f32_e32 v25, v25
	v_exp_f32_e32 v33, v33
	v_pk_add_f32 v[18:19], v[18:19], v[152:153]
	v_pk_add_f32 v[26:27], v[26:27], v[152:153]
	v_pk_add_f32 v[20:21], v[20:21], v[152:153]
	v_pk_add_f32 v[28:29], v[28:29], v[152:153]
	v_pk_add_f32 v[22:23], v[22:23], v[152:153]
	v_pk_add_f32 v[30:31], v[30:31], v[152:153]
	v_pk_add_f32 v[24:25], v[24:25], v[152:153]
	v_pk_add_f32 v[32:33], v[32:33], v[152:153]
	v_rcp_f32_e32 v18, v18
	v_rcp_f32_e32 v26, v26
	v_rcp_f32_e32 v19, v19
	v_rcp_f32_e32 v27, v27
	v_rcp_f32_e32 v20, v20
	v_rcp_f32_e32 v28, v28
	v_rcp_f32_e32 v21, v21
	v_rcp_f32_e32 v29, v29
	v_rcp_f32_e32 v22, v22
	v_rcp_f32_e32 v30, v30
	v_rcp_f32_e32 v23, v23
	v_rcp_f32_e32 v31, v31
	v_rcp_f32_e32 v24, v24
	v_rcp_f32_e32 v32, v32
	v_rcp_f32_e32 v25, v25
	v_rcp_f32_e32 v33, v33
	v_pk_mul_f32 v[84:85], v[84:85], v[18:19]
	v_pk_mul_f32 v[92:93], v[92:93], v[26:27]
	v_pk_mul_f32 v[86:87], v[86:87], v[20:21]
	v_pk_mul_f32 v[94:95], v[94:95], v[28:29]
	v_pk_mul_f32 v[88:89], v[88:89], v[22:23]
	v_pk_mul_f32 v[96:97], v[96:97], v[30:31]
	v_pk_mul_f32 v[90:91], v[90:91], v[24:25]
	v_pk_mul_f32 v[98:99], v[98:99], v[32:33]
	s_cmp_lt_u32 s7, 2
	s_cbranch_scc0 .Lp2c_nonorm_6
	v_pk_mul_f32 v[18:19], v[84:85], v[84:85]
	v_pk_mul_f32 v[26:27], v[92:93], v[92:93]
	v_pk_fma_f32 v[18:19], v[86:87], v[86:87], v[18:19]
	v_pk_fma_f32 v[26:27], v[94:95], v[94:95], v[26:27]
	v_pk_fma_f32 v[18:19], v[88:89], v[88:89], v[18:19]
	v_pk_fma_f32 v[26:27], v[96:97], v[96:97], v[26:27]
	v_pk_fma_f32 v[18:19], v[90:91], v[90:91], v[18:19]
	v_pk_fma_f32 v[26:27], v[98:99], v[98:99], v[26:27]
	v_add_f32_e32 v34, v18, v19
	v_add_f32_e32 v40, v26, v27
	s_nop 0
	v_add_f32_dpp v34, v34, v34 quad_perm:[1,0,3,2] row_mask:0xf bank_mask:0xf
	v_add_f32_dpp v40, v40, v40 quad_perm:[1,0,3,2] row_mask:0xf bank_mask:0xf
	s_nop 0
	v_add_f32_dpp v34, v34, v34 quad_perm:[2,3,0,1] row_mask:0xf bank_mask:0xf
	v_add_f32_dpp v40, v40, v40 quad_perm:[2,3,0,1] row_mask:0xf bank_mask:0xf
	s_nop 0
	v_add_f32_dpp v34, v34, v34 row_half_mirror row_mask:0xf bank_mask:0xf
	v_add_f32_dpp v40, v40, v40 row_half_mirror row_mask:0xf bank_mask:0xf
	s_nop 0
	v_add_f32_dpp v34, v34, v34 row_mirror row_mask:0xf bank_mask:0xf
	v_add_f32_dpp v40, v40, v40 row_mirror row_mask:0xf bank_mask:0xf
	v_add_f32_e32 v34, 0x358637bd, v34
	v_add_f32_e32 v40, 0x358637bd, v40
	v_rsq_f32_e32 v34, v34
	v_rsq_f32_e32 v40, v40
	s_nop 0
	v_mul_f32_e32 v34, v1, v34
	v_mul_f32_e32 v40, v1, v40
	s_nop 0
	v_pk_mul_f32 v[84:85], v[84:85], v[34:35] op_sel_hi:[1,0]
	v_pk_mul_f32 v[86:87], v[86:87], v[34:35] op_sel_hi:[1,0]
	v_pk_mul_f32 v[88:89], v[88:89], v[34:35] op_sel_hi:[1,0]
	v_pk_mul_f32 v[90:91], v[90:91], v[34:35] op_sel_hi:[1,0]
	v_pk_mul_f32 v[92:93], v[92:93], v[40:41] op_sel_hi:[1,0]
	v_pk_mul_f32 v[94:95], v[94:95], v[40:41] op_sel_hi:[1,0]
	v_pk_mul_f32 v[96:97], v[96:97], v[40:41] op_sel_hi:[1,0]
	v_pk_mul_f32 v[98:99], v[98:99], v[40:41] op_sel_hi:[1,0]

; __device__ __forceinline__ float fast_sigmoid(float x) { return __builtin_amdgcn_rcpf(1.f + __builtin_amdgcn_exp2f(-1.4426950408889634f * x)); }
; template <int SKIP>
; __device__ __forceinline__ void p2_chunk_prep_fast(Frame& F, const Args& a) {
;     ...
;                 for (int i4 = 0; i4 < 4; ++i4) { const int ii = 4 * hb + i4;
;                     float v[8];
; #pragma unroll
;                     for (int j = 0; j < 8; ++j) v[j] = 0.f;
; #pragma unroll
;                     for (int kk = 0; kk < 4; ++kk) { f32x4 x0, x1; pg8::unpack8(raw.x[ii + kk], x0, x1);
; #pragma unroll
;                         for (int j = 0; j < 4; ++j) { v[j] += cwr[2 * kk][j] * x0[j]; v[4 + j] += cwr[2 * kk + 1][j] * x1[j]; } }
; #pragma unroll
;                     for (int j = 0; j < 8; ++j) v[j] = v[j] * pg8::fast_sigmoid(v[j]);
;                     if (which < 2) { float ss = 0.f;
; #pragma unroll
;                         for (int j = 0; j < 8; ++j) ss += v[j] * v[j];
;                         ss += __shfl_xor(ss, 1); ss += __shfl_xor(ss, 2); ss += __shfl_xor(ss, 4); ss += __shfl_xor(ss, 8);
;                         const float rs = rsqrtf(ss + EPS) * (which == 0 ? 0.08838834764831845f : 1.f);
; #pragma unroll
;                         for (int j = 0; j < 8; ++j) v[j] *= rs; }
.Lp2c_norow_7:
	v_pk_fma_f32 v[84:85], v[46:47], v[208:209], 0 op_sel_hi:[1,1,0]
	v_pk_fma_f32 v[92:93], v[46:47], v[216:217], 0 op_sel_hi:[1,1,0]
	v_pk_fma_f32 v[86:87], v[48:49], v[210:211], 0 op_sel_hi:[1,1,0]
	v_pk_fma_f32 v[94:95], v[48:49], v[218:219], 0 op_sel_hi:[1,1,0]
	v_pk_fma_f32 v[88:89], v[50:51], v[212:213], 0 op_sel_hi:[1,1,0]
	v_pk_fma_f32 v[96:97], v[50:51], v[220:221], 0 op_sel_hi:[1,1,0]
	v_pk_fma_f32 v[90:91], v[52:53], v[214:215], 0 op_sel_hi:[1,1,0]
	v_pk_fma_f32 v[98:99], v[52:53], v[222:223], 0 op_sel_hi:[1,1,0]
	v_pk_fma_f32 v[84:85], v[54:55], v[216:217], v[84:85]
	v_pk_fma_f32 v[92:93], v[54:55], v[224:225], v[92:93]
	v_pk_fma_f32 v[86:87], v[56:57], v[218:219], v[86:87]
	v_pk_fma_f32 v[94:95], v[56:57], v[226:227], v[94:95]
	v_pk_fma_f32 v[88:89], v[58:59], v[220:221], v[88:89]
	v_pk_fma_f32 v[96:97], v[58:59], v[228:229], v[96:97]
	v_pk_fma_f32 v[90:91], v[60:61], v[222:223], v[90:91]
	v_pk_fma_f32 v[98:99], v[60:61], v[230:231], v[98:99]
	v_pk_fma_f32 v[84:85], v[62:63], v[224:225], v[84:85]
	v_pk_fma_f32 v[92:93], v[62:63], v[232:233], v[92:93]
	v_pk_fma_f32 v[86:87], v[64:65], v[226:227], v[86:87]
	v_pk_fma_f32 v[94:95], v[64:65], v[234:235], v[94:95]
	v_pk_fma_f32 v[88:89], v[66:67], v[228:229], v[88:89]
	v_pk_fma_f32 v[96:97], v[66:67], v[236:237], v[96:97]
	v_pk_fma_f32 v[90:91], v[68:69], v[230:231], v[90:91]
	v_pk_fma_f32 v[98:99], v[68:69], v[238:239], v[98:99]
	v_pk_fma_f32 v[84:85], v[70:71], v[232:233], v[84:85]
	v_pk_fma_f32 v[92:93], v[70:71], v[240:241], v[92:93]
	v_pk_fma_f32 v[86:87], v[72:73], v[234:235], v[86:87]
	v_pk_fma_f32 v[94:95], v[72:73], v[242:243], v[94:95]
	v_pk_fma_f32 v[88:89], v[74:75], v[236:237], v[88:89]
	v_pk_fma_f32 v[96:97], v[74:75], v[244:245], v[96:97]
	v_pk_fma_f32 v[90:91], v[76:77], v[238:239], v[90:91]
	v_pk_fma_f32 v[98:99], v[76:77], v[246:247], v[98:99]
	v_pk_mul_f32 v[18:19], v[84:85], v[100:101]
	v_pk_mul_f32 v[26:27], v[92:93], v[100:101]
	v_pk_mul_f32 v[20:21], v[86:87], v[100:101]
	v_pk_mul_f32 v[28:29], v[94:95], v[100:101]
	v_pk_mul_f32 v[22:23], v[88:89], v[100:101]
	v_pk_mul_f32 v[30:31], v[96:97], v[100:101]
	v_pk_mul_f32 v[24:25], v[90:91], v[100:101]
	v_pk_mul_f32 v[32:33], v[98:99], v[100:101]
	v_exp_f32_e32 v18, v18
	v_exp_f32_e32 v26, v26
	v_exp_f32_e32 v19, v19
	v_exp_f32_e32 v27, v27
	v_exp_f32_e32 v20, v20
	v_exp_f32_e32 v28, v28
	v_exp_f32_e32 v21, v21
	v_exp_f32_e32 v29, v29
	v_exp_f32_e32 v22, v22
	v_exp_f32_e32 v30, v30
	v_exp_f32_e32 v23, v23
	v_exp_f32_e32 v31, v31
	v_exp_f32_e32 v24, v24
	v_exp_f32_e32 v32, v32
	v_exp_f32_e32 v25, v25
	v_exp_f32_e32 v33, v33
	v_pk_add_f32 v[18:19], v[18:19], v[152:153]
	v_pk_add_f32 v[26:27], v[26:27], v[152:153]
	v_pk_add_f32 v[20:21], v[20:21], v[152:153]
	v_pk_add_f32 v[28:29], v[28:29], v[152:153]
	v_pk_add_f32 v[22:23], v[22:23], v[152:153]
	v_pk_add_f32 v[30:31], v[30:31], v[152:153]
	v_pk_add_f32 v[24:25], v[24:25], v[152:153]
	v_pk_add_f32 v[32:33], v[32:33], v[152:153]
	v_rcp_f32_e32 v18, v18
	v_rcp_f32_e32 v26, v26
	v_rcp_f32_e32 v19, v19
	v_rcp_f32_e32 v27, v27
	v_rcp_f32_e32 v20, v20
	v_rcp_f32_e32 v28, v28
	v_rcp_f32_e32 v21, v21
	v_rcp_f32_e32 v29, v29
	v_rcp_f32_e32 v22, v22
	v_rcp_f32_e32 v30, v30
	v_rcp_f32_e32 v23, v23
	v_rcp_f32_e32 v31, v31
	v_rcp_f32_e32 v24, v24
	v_rcp_f32_e32 v32, v32
	v_rcp_f32_e32 v25, v25
	v_rcp_f32_e32 v33, v33
	v_pk_mul_f32 v[84:85], v[84:85], v[18:19]
	v_pk_mul_f32 v[92:93], v[92:93], v[26:27]
	v_pk_mul_f32 v[86:87], v[86:87], v[20:21]
	v_pk_mul_f32 v[94:95], v[94:95], v[28:29]
	v_pk_mul_f32 v[88:89], v[88:89], v[22:23]
	v_pk_mul_f32 v[96:97], v[96:97], v[30:31]
	v_pk_mul_f32 v[90:91], v[90:91], v[24:25]
	v_pk_mul_f32 v[98:99], v[98:99], v[32:33]
	s_cmp_lt_u32 s7, 2
	s_cbranch_scc0 .Lp2c_nonorm_8
	v_pk_mul_f32 v[18:19], v[84:85], v[84:85]
	v_pk_mul_f32 v[26:27], v[92:93], v[92:93]
	v_pk_fma_f32 v[18:19], v[86:87], v[86:87], v[18:19]
	v_pk_fma_f32 v[26:27], v[94:95], v[94:95], v[26:27]
	v_pk_fma_f32 v[18:19], v[88:89], v[88:89], v[18:19]
	v_pk_fma_f32 v[26:27], v[96:97], v[96:97], v[26:27]
	v_pk_fma_f32 v[18:19], v[90:91], v[90:91], v[18:19]
	v_pk_fma_f32 v[26:27], v[98:99], v[98:99], v[26:27]
	v_add_f32_e32 v34, v18, v19
	v_add_f32_e32 v40, v26, v27
	s_nop 0
	v_add_f32_dpp v34, v34, v34 quad_perm:[1,0,3,2] row_mask:0xf bank_mask:0xf
	v_add_f32_dpp v40, v40, v40 quad_perm:[1,0,3,2] row_mask:0xf bank_mask:0xf
	s_nop 0
	v_add_f32_dpp v34, v34, v34 quad_perm:[2,3,0,1] row_mask:0xf bank_mask:0xf
	v_add_f32_dpp v40, v40, v40 quad_perm:[2,3,0,1] row_mask:0xf bank_mask:0xf
	s_nop 0
	v_add_f32_dpp v34, v34, v34 row_half_mirror row_mask:0xf bank_mask:0xf
	v_add_f32_dpp v40, v40, v40 row_half_mirror row_mask:0xf bank_mask:0xf
	s_nop 0
	v_add_f32_dpp v34, v34, v34 row_mirror row_mask:0xf bank_mask:0xf
	v_add_f32_dpp v40, v40, v40 row_mirror row_mask:0xf bank_mask:0xf
	v_add_f32_e32 v34, 0x358637bd, v34
	v_add_f32_e32 v40, 0x358637bd, v40
	v_rsq_f32_e32 v34, v34
	v_rsq_f32_e32 v40, v40
	s_nop 0
	v_mul_f32_e32 v34, v1, v34
	v_mul_f32_e32 v40, v1, v40
	s_nop 0
	v_pk_mul_f32 v[84:85], v[84:85], v[34:35] op_sel_hi:[1,0]
	v_pk_mul_f32 v[86:87], v[86:87], v[34:35] op_sel_hi:[1,0]
	v_pk_mul_f32 v[88:89], v[88:89], v[34:35] op_sel_hi:[1,0]
	v_pk_mul_f32 v[90:91], v[90:91], v[34:35] op_sel_hi:[1,0]
	v_pk_mul_f32 v[92:93], v[92:93], v[40:41] op_sel_hi:[1,0]
	v_pk_mul_f32 v[94:95], v[94:95], v[40:41] op_sel_hi:[1,0]
	v_pk_mul_f32 v[96:97], v[96:97], v[40:41] op_sel_hi:[1,0]
	v_pk_mul_f32 v[98:99], v[98:99], v[40:41] op_sel_hi:[1,0]

; #define LAS __attribute__((address_space(3)))
; template <int SKIP>
; __device__ __forceinline__ void p2_chunk_prep_fast(Frame& F, const Args& a) {
;     ...
;         PREP_LOAD(raw, cu + 1 < u_hi ? cu + 1 : cu);
;         const float gl = gc[63];
;         if (!(SKIP & 2)) {
;             const int kind = w >> 2, ti = w & 3;
;             bf16x8_t af[4];
; #pragma unroll
;             for (int ks = 0; ks < 4; ++ks) af[ks] = *(const LAS bf16x8_t*)(L + L_KS + (16 * ti + fr) * QS_LD + (32 * ks + 8 * fq) * 2);
.LBB0_671:
	s_add_i32 s59, s84, 1
	s_cmp_ge_i32 s59, s16
	s_cselect_b64 s[8:9], -1, 0
	s_cmp_lt_i32 s59, s16
	s_cselect_b32 s6, s59, s84
	s_mul_hi_i32 s7, s6, 0x3e0f83e1
	s_ashr_i32 s85, s7, 3
	s_lshr_b32 s86, s7, 31
	s_add_i32 s85, s85, s86
	s_mul_i32 s87, s85, 33
	s_sub_i32 s87, s6, s87
	s_ashr_i32 s6, s85, 31
	s_lshr_b32 s6, s6, 28
	s_add_i32 s6, s85, s6
	s_and_b32 s6, s6, -16
	s_sub_i32 s6, s85, s6
	s_lshl_b32 s90, s6, 2
	v_mov_b32_e32 v249, s90
	global_load_dword v252, v249, s[46:47]
	global_load_dword v253, v249, s[48:49]
	s_lshl_b32 s85, s6, 7
	s_lshr_b32 s7, s7, 7
	s_add_i32 s85, s85, s58
	s_add_i32 s7, s7, s86
	v_or_b32_e32 v4, s85, v119
	s_lshl_b32 s85, s87, 6
	s_sub_i32 s86, s85, 51
	s_lshl_b32 s7, s7, 11
	v_lshl_add_u32 v3, v78, 3, s86
	s_add_i32 s7, s7, -16
	v_mov_b32_e32 v46, s7
	v_cmp_lt_i32_e32 vcc, 15, v3
	v_ashrrev_i32_e32 v5, 31, v4
	v_max_i32_e32 v6, 0, v3
	v_cndmask_b32_e32 v7, v112, v46, vcc
	v_cmp_lt_i32_e32 vcc, 14, v3
	v_lshl_add_u64 v[4:5], v[4:5], 1, s[18:19]
	v_add_u32_e32 v6, v7, v6
	v_max_i32_e32 v8, -1, v3
	v_cndmask_b32_e32 v9, v112, v46, vcc
	v_mad_i64_i32 v[6:7], s[86:87], v6, s55, v[4:5]
	v_add3_u32 v8, v8, v9, 1
	s_waitcnt lgkmcnt(0)
	s_barrier
	v_mad_i64_i32 v[8:9], s[86:87], v8, s55, v[4:5]
	global_load_dwordx4 v[30:33], v[6:7], off nt
	global_load_dwordx4 v[38:41], v[8:9], off nt
	v_or_b32_e32 v6, 2, v3
	v_cmp_lt_i32_e32 vcc, 15, v6
	v_max_i32_e32 v7, 0, v6
	v_max_i32_e32 v8, -3, v3
	v_cndmask_b32_e32 v6, v112, v46, vcc
	v_cmp_lt_i32_e32 vcc, 12, v3
	v_add_u32_e32 v6, v6, v7
	v_mad_i64_i32 v[6:7], s[86:87], v6, s55, v[4:5]
	v_cndmask_b32_e32 v9, v112, v46, vcc
	v_add3_u32 v8, v8, v9, 3
	v_cmp_lt_i32_e32 vcc, 11, v3
	v_mad_i64_i32 v[8:9], s[86:87], v8, s55, v[4:5]
	global_load_dwordx4 v[34:37], v[6:7], off nt
	global_load_dwordx4 v[42:45], v[8:9], off nt
	v_max_i32_e32 v6, -4, v3
	v_cndmask_b32_e32 v7, v112, v46, vcc
	v_cmp_lt_i32_e32 vcc, 10, v3
	v_add3_u32 v6, v6, v7, 4
	v_max_i32_e32 v8, -5, v3
	v_cndmask_b32_e32 v9, v112, v46, vcc
	v_mad_i64_i32 v[6:7], s[86:87], v6, s55, v[4:5]
	v_add3_u32 v8, v8, v9, 5
	v_cmp_lt_i32_e32 vcc, 9, v3
	v_mad_i64_i32 v[8:9], s[86:87], v8, s55, v[4:5]
	global_load_dwordx4 v[26:29], v[6:7], off nt
	global_load_dwordx4 v[22:25], v[8:9], off nt
	v_max_i32_e32 v6, -6, v3
	v_cndmask_b32_e32 v7, v112, v46, vcc
	v_cmp_lt_i32_e32 vcc, 8, v3
	v_add3_u32 v6, v6, v7, 6
	v_max_i32_e32 v8, -7, v3
	v_cndmask_b32_e32 v9, v112, v46, vcc
	v_mad_i64_i32 v[6:7], s[86:87], v6, s55, v[4:5]
	v_add3_u32 v8, v8, v9, 7
	v_cmp_lt_i32_e32 vcc, 7, v3
	v_mad_i64_i32 v[8:9], s[86:87], v8, s55, v[4:5]
	global_load_dwordx4 v[18:21], v[6:7], off nt
	global_load_dwordx4 v[14:17], v[8:9], off nt
	v_cndmask_b32_e32 v7, v112, v46, vcc
	v_cmp_lt_i32_e32 vcc, 6, v3
	v_max_i32_e32 v6, -8, v3
	v_max_i32_e32 v8, -9, v3
	v_cndmask_b32_e32 v9, v112, v46, vcc
	v_cmp_lt_i32_e32 vcc, 5, v3
	v_max_i32_e32 v47, -10, v3
	v_add_u32_e32 v2, s85, v2
	v_cndmask_b32_e32 v3, v112, v46, vcc
	v_add3_u32 v6, v6, v7, 8
	v_add3_u32 v8, v8, v9, 9
	v_add3_u32 v3, v47, v3, 10
	v_cmp_lt_i32_e32 vcc, 15, v2
	v_mad_i64_i32 v[6:7], s[86:87], v6, s55, v[4:5]
	v_mad_i64_i32 v[8:9], s[86:87], v8, s55, v[4:5]
	v_mad_i64_i32 v[4:5], s[86:87], v3, s55, v[4:5]
	v_max_i32_e32 v3, 0, v2
	v_cndmask_b32_e32 v2, v112, v46, vcc
	v_add_u32_e32 v2, v2, v3
	v_ashrrev_i32_e32 v3, 31, v2
	v_lshlrev_b64 v[2:3], 7, v[2:3]
	v_lshl_add_u64 v[2:3], s[20:21], 0, v[2:3]
	s_ashr_i32 s7, s6, 31
	global_load_dwordx4 v[10:13], v[6:7], off nt
	s_nop 0
	global_load_dwordx4 v[6:9], v[8:9], off nt
	v_lshl_add_u64 v[46:47], s[6:7], 2, v[2:3]
	global_load_dwordx4 v[2:5], v[4:5], off nt
	s_nop 0
	global_load_dword v106, v[46:47], off
	global_load_dword v81, v[46:47], off offset:64
	v_and_b32_e32 v66, -16, v117
	v_or_b32_e32 v47, s61, v83
	v_add_u32_e32 v72, 0, v66
	v_mov_b32_e32 v46, s62
	v_mad_u32_u24 v47, v47, s28, v72
	ds_read_b32 v71, v46
	ds_read_b128 v[58:61], v47 offset:17408
	ds_read_b128 v[54:57], v47 offset:17472
	ds_read_b128 v[50:53], v47 offset:17536
	ds_read_b128 v[46:49], v47 offset:17600
	v_lshlrev_b32_e32 v67, 2, v118
	v_add_u32_e32 v62, s61, v67
	s_ashr_i32 s85, s84, 31
	v_lshlrev_b32_e32 v63, 4, v62
	v_lshlrev_b32_e32 v62, 1, v62
	s_lshl_b64 s[86:87], s[84:85], 13
	v_readlane_b32 s6, v255, 34
	v_and_or_b32 v62, v62, 48, v83
	s_add_u32 s88, s6, s86
	v_readlane_b32 s6, v255, 35
	v_lshlrev_b32_e32 v69, 4, v118
	v_and_b32_e32 v63, 0xfffffe00, v63
	v_lshlrev_b32_e32 v62, 3, v62
	v_and_b32_e32 v68, 4, v67
	s_addc_u32 s89, s6, s87
	v_add_u32_e32 v75, s97, v69
	v_or3_b32 v62, v62, v63, v68
	s_mov_b64 s[6:7], -1
	v_readlane_b32 s100, v255, 19
	s_cmp_eq_u32 s100, 4
	s_cbranch_scc1 .Lst2_skip1
	s_cmp_eq_u32 s100, 0
	s_cbranch_scc1 .Lst2_do1
	s_cmp_eq_u32 s100, 2
	s_cselect_b64 s[6:7], 0, s[6:7]
	s_and_b64 vcc, exec, s[38:39]
	s_cbranch_vccz .LBB0_675

; #define LAS __attribute__((address_space(3)))
; __device__ __forceinline__ u32x2_t pack4bf(f32x4 v) { u32x2_t r; r.x = pg8::cvt_pk_bf16(v[0], v[1]); r.y = pg8::cvt_pk_bf16(v[2], v[3]); return r; }
; __device__ __forceinline__ int frag_off(int row, int k, int ksteps) { return ((row >> 4) * ksteps + (k >> 5)) * 512 + (((k >> 3) & 3) * 16 + (row & 15)) * 8 + (k & 7); }
; template <int SKIP>
; __device__ __forceinline__ void p2_chunk_prep_fast(Frame& F, const Args& a) {
;     ...
;                     const int i = 16 * tj + fr; u32x2_t o = (u32x2_t){0u, 0u};
;                     if (tj >= ti) {
;                         f32x4 acc = (f32x4){0.f, 0.f, 0.f, 0.f};
; #pragma unroll
;                         for (int ks = 0; ks < 4; ++ks) acc = __builtin_amdgcn_mfma_f32_16x16x32_bf16(af[ks], *(const LAS bf16x8_t*)(L + L_QS + (16 * tj + fr) * QS_LD + (32 * ks + 8 * fq) * 2), acc, 0, 0, 0);
;                         const float gi = gc[i]; const f32x4 gj4 = *(const LAS f32x4*)(gc + 16 * ti + 4 * fq);
; #pragma unroll
;                         for (int r = 0; r < 4; ++r) { const float m = (tj > ti || 4 * fq + r <= fr) ? 1.f : 0.f; acc[r] = acc[r] * __expf(fminf(gi - gj4[r], 0.f)) * m; }
;                         o = pack4bf(acc);
;                     }
;                     *(u32x2_t*)(oQK + frag_off(i, 16 * ti + 4 * fq, 2)) = o;
.LBB0_674:
	v_ashrrev_i32_e32 v63, 31, v62
	v_lshl_add_u64 v[76:77], v[62:63], 1, s[88:89]
	s_cmp_eq_u32 s100, 0
	s_cselect_b64 s[6:7], -1, 0
	s_cmp_eq_u32 s100, 6
	s_cselect_b64 s[6:7], -1, s[6:7]
	global_store_dwordx2 v[76:77], v[64:65], off
	s_branch .LBB0_675

; #define LAS __attribute__((address_space(3)))
; __device__ __forceinline__ u32x2_t pack4bf(f32x4 v) { u32x2_t r; r.x = pg8::cvt_pk_bf16(v[0], v[1]); r.y = pg8::cvt_pk_bf16(v[2], v[3]); return r; }
; __device__ __forceinline__ int frag_off(int row, int k, int ksteps) { return ((row >> 4) * ksteps + (k >> 5)) * 512 + (((k >> 3) & 3) * 16 + (row & 15)) * 8 + (k & 7); }
; template <int SKIP>
; __device__ __forceinline__ void p2_chunk_prep_fast(Frame& F, const Args& a) {
;     ...
; #pragma unroll
;             for (int tj = 0; tj < 4; ++tj) {
;                 if (kind == 0) {
;                     if (tj > ti) continue;
;                     f32x4 acc = (f32x4){0.f, 0.f, 0.f, 0.f};
; #pragma unroll
;                     for (int ks = 0; ks < 4; ++ks) acc = __builtin_amdgcn_mfma_f32_16x16x32_bf16(af[ks], *(const LAS bf16x8_t*)(L + L_KS + (16 * tj + fr) * QS_LD + (32 * ks + 8 * fq) * 2), acc, 0, 0, 0);
;                     const int j = 16 * tj + fr; const float gj = gc[j]; const f32x4 gi4 = *(const LAS f32x4*)(gc + 16 * ti + 4 * fq), bi4 = *(const LAS f32x4*)(beta + 16 * ti + 4 * fq);
; #pragma unroll
;                     for (int r = 0; r < 4; ++r) { const int i = 16 * ti + 4 * fq + r; const float m = (tj < ti || fr < 4 * fq + r) ? 1.f : 0.f; Am[i * AM_LD + j] = acc[r] * bi4[r] * __expf(fminf(gi4[r] - gj, 0.f)) * m; }
;                 } else {
;                     const int i = 16 * tj + fr; u32x2_t o = (u32x2_t){0u, 0u};
;                     if (tj >= ti) {
;                         f32x4 acc = (f32x4){0.f, 0.f, 0.f, 0.f};
; #pragma unroll
;                         for (int ks = 0; ks < 4; ++ks) acc = __builtin_amdgcn_mfma_f32_16x16x32_bf16(af[ks], *(const LAS bf16x8_t*)(L + L_QS + (16 * tj + fr) * QS_LD + (32 * ks + 8 * fq) * 2), acc, 0, 0, 0);
;                         const float gi = gc[i]; const f32x4 gj4 = *(const LAS f32x4*)(gc + 16 * ti + 4 * fq);
; #pragma unroll
;                         for (int r = 0; r < 4; ++r) { const float m = (tj > ti || 4 * fq + r <= fr) ? 1.f : 0.f; acc[r] = acc[r] * __expf(fminf(gi - gj4[r], 0.f)) * m; }
;                         o = pack4bf(acc);
;                     }
;                     *(u32x2_t*)(oQK + frag_off(i, 16 * ti + 4 * fq, 2)) = o;
.LBB0_675:
	v_add_u32_e32 v73, s63, v69
	v_add_u32_e32 v74, s64, v69
	v_add_u32_e32 v69, s54, v67
	s_cmp_lg_u32 s100, 6
	s_cbranch_scc1 .Lst2_n6
	v_subrev_u32_e32 v69, 64, v69
	v_subrev_u32_e32 v73, 0x100, v73
	v_subrev_u32_e32 v74, 0x100, v74
.Lst2_n6:
	s_and_b64 vcc, exec, s[6:7]
	v_lshlrev_b32_e32 v70, 2, v83
	s_cbranch_vccz .LBB0_677
	v_mad_u32_u24 v63, v83, s28, v72
	ds_read_b128 v[84:87], v63 offset:17408
	ds_read_b128 v[88:91], v63 offset:17472
	v_cmp_lt_i32_e32 vcc, v83, v67
	s_or_b64 s[6:7], s[70:71], vcc
	v_cmp_le_i32_e32 vcc, v83, v67
	s_waitcnt lgkmcnt(1)
	v_mfma_f32_16x16x32_bf16 v[84:87], v[58:61], v[84:87], 0
	v_cndmask_b32_e64 v64, 0, 1.0, s[6:7]
	s_or_b64 s[6:7], s[70:71], vcc
	s_waitcnt lgkmcnt(0)
	v_mfma_f32_16x16x32_bf16 v[84:87], v[54:57], v[88:91], v[84:87]
	ds_read_b128 v[88:91], v63 offset:17536
	s_waitcnt lgkmcnt(0)
	v_mfma_f32_16x16x32_bf16 v[84:87], v[50:53], v[88:91], v[84:87]
	ds_read_b128 v[88:91], v63 offset:17600
	v_add_u32_e32 v63, 0, v70
	v_add_u32_e32 v63, 0x20500, v63
	s_waitcnt lgkmcnt(0)
	v_mfma_f32_16x16x32_bf16 v[84:87], v[46:49], v[88:91], v[84:87]
	ds_read_b32 v63, v63
	ds_read_b128 v[88:91], v73
	ds_read_b128 v[92:95], v74
	s_waitcnt lgkmcnt(1)
	v_sub_f32_e32 v76, v88, v63
	v_sub_f32_e32 v78, v89, v63
	v_min_f32_e32 v76, 0, v76
	v_min_f32_e32 v78, 0, v78
	v_mul_f32_e32 v76, 0x3fb8aa3b, v76
	v_mul_f32_e32 v78, 0x3fb8aa3b, v78
	v_exp_f32_e32 v76, v76
	v_exp_f32_e32 v78, v78
	s_waitcnt lgkmcnt(0)
	v_mul_f32_e32 v65, v84, v92
	v_mul_f32_e32 v77, v85, v93
	v_mul_f32_e32 v65, v65, v76
	v_cndmask_b32_e64 v76, 0, 1.0, s[6:7]
	v_mul_f32_e32 v77, v77, v78
	v_mul_f32_e32 v76, v76, v77
	v_sub_f32_e32 v77, v90, v63
	v_min_f32_e32 v77, 0, v77
	v_mul_f32_e32 v64, v64, v65
	v_mul_lo_u32 v65, v69, s28
	v_mul_f32_e32 v77, 0x3fb8aa3b, v77
	v_add3_u32 v65, s29, v70, v65
	v_exp_f32_e32 v77, v77
	ds_write2_b32 v65, v64, v76 offset1:68
	v_or_b32_e32 v64, 2, v67
	v_sub_f32_e32 v63, v91, v63
	v_cmp_lt_i32_e32 vcc, v83, v64
	v_min_f32_e32 v63, 0, v63
	s_or_b64 s[6:7], s[70:71], vcc
	v_mul_f32_e32 v76, v86, v94
	v_mul_f32_e32 v63, 0x3fb8aa3b, v63
	v_cndmask_b32_e64 v64, 0, 1.0, s[6:7]
	v_mul_f32_e32 v76, v76, v77
	v_exp_f32_e32 v63, v63
	v_mul_f32_e32 v64, v64, v76
	v_or_b32_e32 v76, 3, v67
	v_cmp_lt_i32_e32 vcc, v83, v76
	s_or_b64 s[6:7], s[70:71], vcc
	v_mul_f32_e32 v77, v87, v95
	v_cndmask_b32_e64 v76, 0, 1.0, s[6:7]
	v_mul_f32_e32 v63, v77, v63
	v_mul_f32_e32 v63, v76, v63
	ds_write2_b32 v65, v64, v63 offset0:136 offset1:204
.LBB0_677:
	v_cndmask_b32_e64 v63, 0, 1, s[38:39]
	v_cmp_ne_u32_e64 s[6:7], 1, v63
	s_mov_b64 s[90:91], -1
	s_cmp_eq_u32 s100, 5
	s_cbranch_scc1 .Lst2_skip3
	s_cmp_eq_u32 s100, 1
	s_cbranch_scc1 .Lst2_do3
	s_andn2_b64 vcc, exec, s[38:39]
	s_cbranch_vccnz .LBB0_681
.Lst2_do3:
	v_mov_b32_e32 v64, 0
	s_andn2_b64 vcc, exec, s[72:73]
	v_mov_b32_e32 v65, 0
	s_cbranch_vccnz .LBB0_680
	v_or_b32_e32 v63, 16, v83
	v_mad_u32_u24 v64, v63, s28, v72
	ds_read_b128 v[84:87], v64
	ds_read_b128 v[88:91], v64 offset:64
	v_lshl_add_u32 v63, v63, 2, 0
	v_add_u32_e32 v63, 0x20500, v63
	v_cmp_gt_i32_e32 vcc, v67, v83
	s_waitcnt lgkmcnt(1)
	v_mfma_f32_16x16x32_bf16 v[84:87], v[58:61], v[84:87], 0
	s_waitcnt lgkmcnt(0)
	v_mfma_f32_16x16x32_bf16 v[84:87], v[54:57], v[88:91], v[84:87]
	ds_read_b128 v[88:91], v64 offset:128
	s_waitcnt lgkmcnt(0)
	v_mfma_f32_16x16x32_bf16 v[84:87], v[50:53], v[88:91], v[84:87]
	ds_read_b128 v[88:91], v64 offset:192
	v_cndmask_b32_e64 v64, 1.0, 0, vcc
	v_cmp_lt_i32_e32 vcc, v67, v83
	s_waitcnt lgkmcnt(0)
	v_mfma_f32_16x16x32_bf16 v[84:87], v[46:49], v[88:91], v[84:87]
	ds_read_b32 v63, v63
	ds_read_b128 v[88:91], v75
	v_cndmask_b32_e64 v64, v64, 1.0, s[68:69]
	s_or_b64 s[90:91], s[68:69], vcc
	s_waitcnt lgkmcnt(0)
	v_sub_f32_e32 v65, v63, v88
	v_min_f32_e32 v65, 0, v65
	v_sub_f32_e32 v76, v63, v89
	v_mul_f32_e32 v65, 0x3fb8aa3b, v65
	v_min_f32_e32 v76, 0, v76
	v_exp_f32_e32 v65, v65
	v_mul_f32_e32 v76, 0x3fb8aa3b, v76
	v_exp_f32_e32 v76, v76
	v_sub_f32_e32 v77, v63, v90
	v_min_f32_e32 v77, 0, v77
	v_mul_f32_e32 v65, v84, v65
	v_mul_f32_e32 v77, 0x3fb8aa3b, v77
	v_mul_f32_e32 v64, v64, v65
	v_cndmask_b32_e64 v65, 0, 1.0, s[90:91]
	v_mul_f32_e32 v76, v85, v76
	v_exp_f32_e32 v77, v77
	v_mul_f32_e32 v65, v65, v76
	v_or_b32_e32 v76, 2, v67
	v_sub_f32_e32 v63, v63, v91
	v_cmp_gt_i32_e32 vcc, v76, v83
	v_min_f32_e32 v63, 0, v63
	v_mul_f32_e32 v63, 0x3fb8aa3b, v63
	v_cndmask_b32_e64 v76, 1.0, 0, vcc
	v_cndmask_b32_e64 v76, v76, 1.0, s[68:69]
	v_mul_f32_e32 v77, v86, v77
	v_exp_f32_e32 v63, v63
	v_mul_f32_e32 v76, v76, v77
	v_or_b32_e32 v77, 3, v67
	v_cmp_gt_i32_e32 vcc, v77, v83
	v_mul_f32_e32 v63, v87, v63
	v_cvt_pk_bf16_f32 v64, v64, v65
	v_cndmask_b32_e64 v77, 1.0, 0, vcc
	v_cndmask_b32_e64 v77, v77, 1.0, s[68:69]
	v_mul_f32_e32 v63, v77, v63
	v_cvt_pk_bf16_f32 v65, v76, v63
.LBB0_680:
	v_ashrrev_i32_e32 v63, 31, v62
	v_lshl_add_u64 v[76:77], v[62:63], 1, s[88:89]
	s_cmp_eq_u32 s100, 1
	s_cselect_b64 s[90:91], -1, 0
	global_store_dwordx2 v[76:77], v[64:65], off offset:2048
	s_branch .LBB0_681
.Lst2_skip3:
	s_mov_b64 s[90:91], 0

; template <int SKIP>
; __device__ __forceinline__ void p2_chunk_prep_fast(Frame& F, const Args& a) {
;     ...
; #pragma unroll
;             for (int tj = 0; tj < 4; ++tj) {
;                 if (kind == 0) {
.LBB0_696:
	s_cmp_lt_u32 s100, 6
	s_cbranch_scc1 .Lst2_r7
	v_add_u32_e32 v69, 64, v69
